# v6 + work stealing across XCD-local E4 queues at the tail + GDN LDS read batching/DPP + prologue Q/K load overlap
# baseline (speedup 1.0000x reference)
; #define LAS __attribute__((address_space(3)))
; __global__ void __launch_bounds__(512, 2) mega_fwd(Params p) {
;     ...
;                         PH_PTRS
;                         LAS int* qslot = (LAS int*)(lds + LDS_BYTES - 64);
;                         for (int rep = 0; rep <= PROBE_E4; ++rep) {
;                         int* ctr = (int*)(ctl + C_QCTR) + e * 64 + rep * 32;
;                         for (;;) {
;                             if (threadIdx.x == 0) *qslot = __hip_atomic_fetch_add(ctr, 1, __ATOMIC_RELAXED, __HIP_MEMORY_SCOPE_AGENT);
.LBB0_3622:
	s_movk_i32 s28, 0x90
	s_or_b64 exec, exec, s[0:1]
	s_mov_b64 s[0:1], s[92:93]
	v_readlane_b32 s4, v255, 23
	s_waitcnt lgkmcnt(0)
	s_barrier
	v_readlane_b32 s5, v255, 24
	s_add_u32 s4, s0, s4
	s_addc_u32 s5, s1, s5
	s_add_u32 s60, s4, 0x404000
	s_addc_u32 s61, s5, 0
	s_getreg_b32 s100, hwreg(HW_REG_XCC_ID, 0, 4)
	s_and_b32 s100, s100, 7
	s_lshl_b32 s100, s100, 2
	s_mov_b32 s32, s60
	s_mov_b32 s75, s61
	s_mov_b32 s31, 0
	s_add_u32 s60, s32, s100
	s_addc_u32 s61, s75, 0
	s_add_u32 s62, s0, 0x11800000
	s_addc_u32 s63, s1, 0
	s_add_u32 s20, s0, 0x14800000
	s_addc_u32 s21, s1, 0
	s_add_u32 s64, s0, 0x17800000
	s_addc_u32 s65, s1, 0
	s_add_u32 s70, s0, 0xb800000
	s_addc_u32 s71, s1, 0
	s_add_u32 s72, s0, 0x19800000
	s_addc_u32 s73, s1, 0
	s_add_u32 s36, s0, 0x1b800000
	s_addc_u32 s37, s1, 0
	s_add_u32 s68, s0, 0x7800000
	s_addc_u32 s69, s1, 0
	s_add_u32 s84, s0, 0x9800000
	s_addc_u32 s85, s1, 0
	s_add_u32 s96, s0, 0x1fa00000
	s_addc_u32 s97, s1, 0
	s_add_u32 s58, s0, 0xf800000
	s_addc_u32 s59, s1, 0
	s_add_u32 s4, s0, 0x17810000
	s_addc_u32 s5, s1, 0
	s_mov_b32 s34, 0x2aaaaaab
	s_movk_i32 s35, 0xff
	s_branch .LBB0_3626

; __device__ __forceinline__ u32x4 pack8(const float* f) { u32x4 o; o.x = pk2(f[0], f[1]); o.y = pk2(f[2], f[3]); o.z = pk2(f[4], f[5]); o.w = pk2(f[6], f[7]); return o; }
; __global__ void __launch_bounds__(512, 2) mega_fwd(Params p) {
;     ...
;                             const int idx = *qslot;
;                             __syncthreads();
;                             if (idx >= 32 + 1024) break;
;                             if (idx < 32 && ZERO_GDN) {
;                                 bf16* Yz = (bf16*)(ws + A_Y); const int zb = idx >> 3, zh = idx & 7;
;                                 const bf16* GQ_ = (const bf16*)(ws + A_GQ); const bf16* GK_ = (const bf16*)(ws + A_GK); const bf16* U_ = (const bf16*)(ws + A_U); const bf16* W_ = (const bf16*)(ws + A_WW); const float* GC_ = (const float*)(ws + A_GC);
;                                 for (int i = threadIdx.x; i < SEQ * 8; i += 512) { const int tk = i >> 3, sgm = i & 7; const size_t tok = (size_t)zb * SEQ + tk; const int nn = tk >> 6, rr = tk & 63;
;                                     float a[8], b_[8], c_[8], d_[8], o_[8];
;                                     unpack8(*(const u32x4*)(GQ_ + tok * 512 + zh * 64 + sgm * 8), a); unpack8(*(const u32x4*)(GK_ + tok * 512 + zh * 64 + sgm * 8), b_);
;                                     unpack8(*(const u32x4*)(U_ + (((size_t)idx * 128 + nn) * 64 + rr) * 64 + sgm * 8), c_); unpack8(*(const u32x4*)(W_ + (((size_t)idx * 128 + nn) * 64 + rr) * 64 + sgm * 8), d_);
;                                     const float gcv = GC_[((size_t)idx * 128 + nn) * 64 + rr]; unpack8(*(const u32x4*)((const bf16*)(ws + A_Z) + tok * 512 + zh * 64 + sgm * 8), a);
;                                     for (int k = 0; k < 8; ++k) o_[k] = a[k] + b_[k] + c_[k] + d_[k] + 0.01f * gcv;
;                                     *(u32x4*)(Yz + tok * 1024 + 512 + zh * 64 + sgm * 8) = pack8(o_); }
;                             } else if (idx < 32) {
;                                 gdn_scan(lds, idx, (const bf16*)(ws + A_GQ), (const bf16*)(ws + A_GK), (const bf16*)(ws + A_U), (const bf16*)(ws + A_WW), (const float*)(ws + A_GC),
;                                          (const bf16*)(ws + A_Z), (const float*)p.in[16] + e * 64, (bf16*)(ws + A_Y));
;                             } else {
;                                 const int a = idx - 32, qb = 31 - (a >> 5), bh = a & 31;
.Lq_small:
	s_add_u32 s8, s8, s100
	s_cmp_gt_i32 s8, 31
	s_cbranch_scc0 .LBB0_3657
	s_sub_i32 s6, s8, 32
	v_mov_b32_e32 v4, v163
	s_lshr_b32 s22, s6, 5
	s_sub_i32 s12, 31, s22
	v_ashrrev_i32_e32 v8, 6, v4
	s_bfe_u32 s23, s8, 0x20003
	v_readfirstlane_b32 s6, v8
	s_lshl_b32 s7, s12, 8
	s_lshl_b32 s13, s23, 13
	s_lshl_b32 s14, s6, 5
	s_and_b32 s9, s8, 7
	s_or_b32 s7, s7, s13
	s_ashr_i32 s6, s14, 31
	v_and_b32_e32 v7, 31, v4
	s_add_u32 s7, s14, s7
	v_or_b32_e32 v104, s7, v7
	v_mov_b64_e32 v[0:1], s[62:63]
	s_addc_u32 s15, s6, 0
	v_mad_u64_u32 v[0:1], s[6:7], v104, s87, v[0:1]
	v_bfe_u32 v6, v4, 5, 1
	v_mad_i32_i24 v1, s15, v220, v1
	s_mul_i32 s80, s9, 0xc0
	v_lshl_add_u64 v[0:1], v[0:1], 0, s[80:81]
	v_lshlrev_b32_e32 v2, 4, v6
	v_mov_b32_e32 v3, v64
	v_lshl_add_u64 v[0:1], v[0:1], 0, v[2:3]
	s_mul_i32 s6, s23, 0xc00000
	flat_load_dwordx4 v[68:71], v[0:1]
	flat_load_dwordx4 v[72:75], v[0:1] offset:32
	flat_load_dwordx4 v[76:79], v[0:1] offset:64
	flat_load_dwordx4 v[80:83], v[0:1] offset:96
	flat_load_dwordx4 v[84:87], v[0:1] offset:128
	flat_load_dwordx4 v[88:91], v[0:1] offset:160
	v_mul_hi_i32 v0, v4, s34
	s_add_u32 s6, s20, s6
	v_lshrrev_b32_e32 v1, 31, v0
	v_ashrrev_i32_e32 v0, 1, v0
	s_addc_u32 s7, s21, 0
	v_add_u32_e32 v9, v0, v1
	s_add_u32 s6, s6, s80
	v_mul_lo_u32 v0, v9, 12
	s_addc_u32 s7, s7, 0
	v_sub_u32_e32 v12, v4, v0
	v_mov_b64_e32 v[0:1], s[6:7]
	v_mad_i64_i32 v[2:3], s[10:11], v9, s87, v[0:1]
	v_lshlrev_b32_e32 v0, 3, v12
	v_ashrrev_i32_e32 v1, 31, v0
	v_lshl_add_u64 v[2:3], v[0:1], 1, v[2:3]
	flat_load_dwordx4 v[92:95], v[2:3]
	v_add_u32_e32 v2, 0x200, v4
	v_mul_hi_i32 v3, v2, s34
	v_lshrrev_b32_e32 v5, 31, v3
	v_ashrrev_i32_e32 v3, 1, v3
	v_add_u32_e32 v10, v3, v5
	v_mul_lo_u32 v3, v10, 12
	v_sub_u32_e32 v13, v2, v3
	v_mov_b32_e32 v66, v64
	v_mov_b32_e32 v67, v64
	s_movk_i32 s10, 0x100
	v_mov_b32_e32 v65, v64
	v_lshlrev_b32_e32 v2, 3, v13
	v_mov_b64_e32 v[98:99], v[66:67]
	v_mov_b32_e32 v105, s15
	v_cmp_lt_i32_e32 vcc, s35, v4
	v_cmp_gt_i32_e64 s[38:39], s10, v4
	v_ashrrev_i32_e32 v3, 31, v2
	v_mov_b64_e32 v[96:97], v[64:65]
	s_and_saveexec_b64 s[10:11], s[38:39]
	s_cbranch_execz .LBB0_3632
	v_mov_b64_e32 v[14:15], s[6:7]
	v_mad_i64_i32 v[14:15], s[24:25], v10, s87, v[14:15]
	v_lshl_add_u64 v[14:15], v[2:3], 1, v[14:15]
	flat_load_dwordx4 v[96:99], v[14:15]

; __global__ void __launch_bounds__(512, 2) mega_fwd(Params p) {
;     ...
;                         for (;;) {
;                             if (threadIdx.x == 0) *qslot = __hip_atomic_fetch_add(ctr, 1, __ATOMIC_RELAXED, __HIP_MEMORY_SCOPE_AGENT);
;                             __syncthreads();
;                             const int idx = *qslot;
;                             __syncthreads();
;                             if (idx >= 32 + 1024) break;
.Lq_exhausted:
	s_add_u32 s31, s31, 1
	s_cmp_ge_u32 s31, 8
	s_cbranch_scc1 .LBB0_3625
	s_add_u32 s100, s100, 4
	s_and_b32 s100, s100, 28
	s_add_u32 s60, s32, s100
	s_addc_u32 s61, s75, 0
	s_branch .LBB0_3626
